# P0 lora-weight conversion: nine per-thread gathers unrolled and issued before one wait (grid 256 fast path, generic loop kept)
# baseline (speedup 1.0000x reference)
; __device__ __forceinline__ unsigned f2bf(float f) { unsigned u = __float_as_uint(f); return (u + 0x7fffu + ((u >> 16) & 1u)) >> 16; }
; __device__ __forceinline__ void phase_prologue(const Params& p, LAS unsigned char* lds) {
;     ...
;     { bf16* WL = (bf16*)(ws + WS_W_LORA); const int gt = blockIdx.x * NTHR + tid, NGT = G * NTHR;
;       for (int i = gt; i < N_LORA * K_LORA; i += NGT) { const int n = i / K_LORA, k = i % K_LORA; float v = 0.f;
;           if (n < 1024) { if (k < 64) v = p.in[I_W2][k * 1024 + n]; }
;           else if (n < 2048) { if (k >= 64 && k < 128) v = p.in[I_A2][(k - 64) * 1024 + (n - 1024)]; }
;           else { if (k >= 128 && k < 288) v = p.in[I_G2][(k - 128) * 1024 + (n - 2048)]; }
;           WL[i] = (bf16)f2bf(v); } }
.LBB0_288:
	s_or_b64 exec, exec, s[0:1]
	v_readlane_b32 s10, v244, 0
	s_nop 3
	s_cmpk_eq_u32 s10, 0x100
	s_cbranch_scc0 .Llora_generic
	v_add_u32_e32 v2, s33, v144
	s_add_u32 s4, s28, 0x2600000
	s_addc_u32 s5, s29, 0
	v_readlane_b32 s44, v244, 22
	v_readlane_b32 s45, v244, 23
	s_mov_b32 s36, 0x2aaaaaab
	s_movk_i32 s39, 0x7fff
	v_mov_b32_e32 v5, 0
	v_mov_b32_e32 v7, 0
	v_mov_b32_e32 v6, v2
	v_mul_hi_i32 v3, v6, s36
	v_ashrrev_i32_e32 v3, 6, v3
	v_mul_u32_u24_e32 v8, 0x180, v3
	v_sub_u32_e32 v8, v6, v8
	v_cmp_gt_u32_e32 vcc, 64, v8
	v_lshl_add_u32 v4, v8, 10, v3
	v_lshl_add_u64 v[8:9], v[4:5], 2, s[78:79]
	v_mov_b32_e32 v245, 0
	s_and_saveexec_b64 s[12:13], vcc
	global_load_dword v245, v[8:9], off
	s_or_b64 exec, exec, s[12:13]
	v_add_u32_e32 v6, 0x20000, v2
	v_mul_hi_i32 v3, v6, s36
	v_ashrrev_i32_e32 v3, 6, v3
	v_mul_u32_u24_e32 v8, 0x180, v3
	v_sub_u32_e32 v8, v6, v8
	v_cmp_gt_u32_e32 vcc, 64, v8
	v_lshl_add_u32 v4, v8, 10, v3
	v_lshl_add_u64 v[8:9], v[4:5], 2, s[78:79]
	v_mov_b32_e32 v246, 0
	s_and_saveexec_b64 s[12:13], vcc
	global_load_dword v246, v[8:9], off
	s_or_b64 exec, exec, s[12:13]
	v_add_u32_e32 v6, 0x40000, v2
	v_mul_hi_i32 v3, v6, s36
	v_ashrrev_i32_e32 v3, 6, v3
	v_mul_u32_u24_e32 v8, 0x180, v3
	v_sub_u32_e32 v8, v6, v8
	v_cmp_gt_u32_e32 vcc, 64, v8
	v_lshl_add_u32 v4, v8, 10, v3
	v_lshl_add_u64 v[8:9], v[4:5], 2, s[78:79]
	v_mov_b32_e32 v247, 0
	s_and_saveexec_b64 s[12:13], vcc
	global_load_dword v247, v[8:9], off
	s_or_b64 exec, exec, s[12:13]
	v_add_u32_e32 v6, 0x60000, v2
	v_mul_hi_i32 v3, v6, s36
	v_ashrrev_i32_e32 v3, 6, v3
	v_mul_u32_u24_e32 v8, 0x180, v3
	v_sub_u32_e32 v8, v6, v8
	v_add_u32_e32 v9, 0xffffffc0, v8
	v_cmp_gt_u32_e32 vcc, 64, v9
	v_lshl_add_u32 v4, v9, 10, v3
	v_add_u32_e32 v4, 0xfffffc00, v4
	v_lshl_add_u64 v[8:9], v[4:5], 2, s[82:83]
	v_mov_b32_e32 v248, 0
	s_and_saveexec_b64 s[12:13], vcc
	global_load_dword v248, v[8:9], off
	s_or_b64 exec, exec, s[12:13]
	v_add_u32_e32 v6, 0x80000, v2
	v_mul_hi_i32 v3, v6, s36
	v_ashrrev_i32_e32 v3, 6, v3
	v_mul_u32_u24_e32 v8, 0x180, v3
	v_sub_u32_e32 v8, v6, v8
	v_add_u32_e32 v9, 0xffffffc0, v8
	v_cmp_gt_u32_e32 vcc, 64, v9
	v_lshl_add_u32 v4, v9, 10, v3
	v_add_u32_e32 v4, 0xfffffc00, v4
	v_lshl_add_u64 v[8:9], v[4:5], 2, s[82:83]
	v_mov_b32_e32 v249, 0
	s_and_saveexec_b64 s[12:13], vcc
	global_load_dword v249, v[8:9], off
	s_or_b64 exec, exec, s[12:13]
	v_add_u32_e32 v6, 0xa0000, v2
	v_mul_hi_i32 v3, v6, s36
	v_ashrrev_i32_e32 v3, 6, v3
	v_mul_u32_u24_e32 v8, 0x180, v3
	v_sub_u32_e32 v8, v6, v8
	v_add_u32_e32 v9, 0xffffffc0, v8
	v_cmp_gt_u32_e32 vcc, 64, v9
	v_lshl_add_u32 v4, v9, 10, v3
	v_add_u32_e32 v4, 0xfffffc00, v4
	v_lshl_add_u64 v[8:9], v[4:5], 2, s[82:83]
	v_mov_b32_e32 v250, 0
	s_and_saveexec_b64 s[12:13], vcc
	global_load_dword v250, v[8:9], off
	s_or_b64 exec, exec, s[12:13]
	v_add_u32_e32 v6, 0xc0000, v2
	v_mul_hi_i32 v3, v6, s36
	v_ashrrev_i32_e32 v3, 6, v3
	v_mul_u32_u24_e32 v8, 0x180, v3
	v_sub_u32_e32 v8, v6, v8
	v_add_u32_e32 v9, 0xffffff80, v8
	s_movk_i32 s38, 0xa0
	v_cmp_gt_u32_e32 vcc, s38, v9
	v_lshl_add_u32 v4, v9, 10, v3
	v_add_u32_e32 v4, 0xfffff800, v4
	v_lshl_add_u64 v[8:9], v[4:5], 2, s[44:45]
	v_mov_b32_e32 v251, 0
	s_and_saveexec_b64 s[12:13], vcc
	global_load_dword v251, v[8:9], off
	s_or_b64 exec, exec, s[12:13]
	v_add_u32_e32 v6, 0xe0000, v2
	v_mul_hi_i32 v3, v6, s36
	v_ashrrev_i32_e32 v3, 6, v3
	v_mul_u32_u24_e32 v8, 0x180, v3
	v_sub_u32_e32 v8, v6, v8
	v_add_u32_e32 v9, 0xffffff80, v8
	s_movk_i32 s38, 0xa0
	v_cmp_gt_u32_e32 vcc, s38, v9
	v_lshl_add_u32 v4, v9, 10, v3
	v_add_u32_e32 v4, 0xfffff800, v4
	v_lshl_add_u64 v[8:9], v[4:5], 2, s[44:45]
	v_mov_b32_e32 v252, 0
	s_and_saveexec_b64 s[12:13], vcc
	global_load_dword v252, v[8:9], off
	s_or_b64 exec, exec, s[12:13]
	v_add_u32_e32 v6, 0x100000, v2
	v_mul_hi_i32 v3, v6, s36
	v_ashrrev_i32_e32 v3, 6, v3
	v_mul_u32_u24_e32 v8, 0x180, v3
	v_sub_u32_e32 v8, v6, v8
	v_add_u32_e32 v9, 0xffffff80, v8
	s_movk_i32 s38, 0xa0
	v_cmp_gt_u32_e32 vcc, s38, v9
	v_lshl_add_u32 v4, v9, 10, v3
	v_add_u32_e32 v4, 0xfffff800, v4
	v_lshl_add_u64 v[8:9], v[4:5], 2, s[44:45]
	v_mov_b32_e32 v253, 0
	s_and_saveexec_b64 s[12:13], vcc
	global_load_dword v253, v[8:9], off
	s_or_b64 exec, exec, s[12:13]
	s_waitcnt vmcnt(0)
	v_mov_b32_e32 v6, v2
	v_bfe_u32 v4, v245, 16, 1
	v_lshl_add_u64 v[8:9], v[6:7], 1, s[4:5]
	v_add3_u32 v4, v245, v4, s39
	global_store_short_d16_hi v[8:9], v4, off
	v_add_u32_e32 v6, 0x20000, v2
	v_bfe_u32 v4, v246, 16, 1
	v_lshl_add_u64 v[8:9], v[6:7], 1, s[4:5]
	v_add3_u32 v4, v246, v4, s39
	global_store_short_d16_hi v[8:9], v4, off
	v_add_u32_e32 v6, 0x40000, v2
	v_bfe_u32 v4, v247, 16, 1
	v_lshl_add_u64 v[8:9], v[6:7], 1, s[4:5]
	v_add3_u32 v4, v247, v4, s39
	global_store_short_d16_hi v[8:9], v4, off
	v_add_u32_e32 v6, 0x60000, v2
	v_bfe_u32 v4, v248, 16, 1
	v_lshl_add_u64 v[8:9], v[6:7], 1, s[4:5]
	v_add3_u32 v4, v248, v4, s39
	global_store_short_d16_hi v[8:9], v4, off
	v_add_u32_e32 v6, 0x80000, v2
	v_bfe_u32 v4, v249, 16, 1
	v_lshl_add_u64 v[8:9], v[6:7], 1, s[4:5]
	v_add3_u32 v4, v249, v4, s39
	global_store_short_d16_hi v[8:9], v4, off
	v_add_u32_e32 v6, 0xa0000, v2
	v_bfe_u32 v4, v250, 16, 1
	v_lshl_add_u64 v[8:9], v[6:7], 1, s[4:5]
	v_add3_u32 v4, v250, v4, s39
	global_store_short_d16_hi v[8:9], v4, off
	v_add_u32_e32 v6, 0xc0000, v2
	v_bfe_u32 v4, v251, 16, 1
	v_lshl_add_u64 v[8:9], v[6:7], 1, s[4:5]
	v_add3_u32 v4, v251, v4, s39
	global_store_short_d16_hi v[8:9], v4, off
	v_add_u32_e32 v6, 0xe0000, v2
	v_bfe_u32 v4, v252, 16, 1
	v_lshl_add_u64 v[8:9], v[6:7], 1, s[4:5]
	v_add3_u32 v4, v252, v4, s39
	global_store_short_d16_hi v[8:9], v4, off
	v_add_u32_e32 v6, 0x100000, v2
	v_bfe_u32 v4, v253, 16, 1
	v_lshl_add_u64 v[8:9], v[6:7], 1, s[4:5]
	v_add3_u32 v4, v253, v4, s39
	global_store_short_d16_hi v[8:9], v4, off
	s_mov_b64 s[0:1], exec
	s_branch .LBB0_305
.Llora_generic:
	v_add_u32_e32 v2, s33, v144
	s_mov_b32 s0, 0x120000
	v_cmp_gt_i32_e32 vcc, s0, v2
	s_and_saveexec_b64 s[0:1], vcc
	s_cbranch_execz .LBB0_305
	v_readlane_b32 s10, v244, 0
	s_add_u32 s4, s28, 0x2600000
	v_readlane_b32 s11, v244, 1
	v_lshlrev_b32_e32 v3, 10, v144
	s_addc_u32 s5, s29, 0
	s_lshl_b32 s18, s10, 9
	v_lshl_add_u32 v6, s96, 19, v3
	s_lshl_b32 s19, s10, 19
	s_mov_b64 s[10:11], 0
	s_mov_b32 s33, 0x2aaaaaab
	s_mov_b32 s36, 0x5ffff
	s_mov_b32 s37, 0xbffff
	s_movk_i32 s38, 0xa0
	v_mov_b32_e32 v5, 0
	s_movk_i32 s39, 0x7fff
	s_mov_b32 s40, 0x11ffff
	s_branch .LBB0_292
